# attention: score waves no longer raise their priority
# speedup vs baseline: 1.0135x; 1.0027x over previous
.LBB0_405:
	v_add_u32_e32 v0, s29, v219
	v_mov_b64_e32 v[2:3], s[6:7]
	s_movk_i32 s8, 0x2800
	v_mad_i64_i32 v[2:3], s[8:9], v0, s8, v[2:3]
	v_or_b32_e32 v0, s28, v161
	v_mul_u32_u24_e32 v0, 0x140, v0
	v_lshlrev_b32_e32 v0, 1, v0
	v_lshl_add_u64 v[32:33], v[2:3], 0, v[0:1]
	s_setprio 0
	v_lshl_add_u64 v[2:3], s[16:17], 0, v[162:163]
	global_load_dwordx4 v[4:7], v[2:3], off offset:48
	global_load_dwordx4 v[8:11], v[2:3], off offset:32
	global_load_dwordx4 v[12:15], v[2:3], off offset:16
	global_load_dwordx4 v[16:19], v[2:3], off
	global_load_dwordx4 v[20:23], v[2:3], off offset:112
	global_load_dwordx4 v[24:27], v[2:3], off offset:96
	global_load_dwordx4 v[28:31], v[2:3], off offset:80
	global_load_dwordx4 v[114:117], v[2:3], off offset:64
	global_load_dwordx4 v[118:121], v[2:3], off offset:144
	global_load_dwordx4 v[122:125], v[2:3], off offset:128
	v_mov_b32_e32 v165, v1
	v_lshl_add_u64 v[32:33], v[32:33], 0, v[164:165]
	global_load_dwordx4 v[34:37], v[32:33], off
	global_load_dwordx4 v[38:41], v[32:33], off offset:32
	global_load_dwordx4 v[42:45], v[32:33], off offset:64
	global_load_dwordx4 v[46:49], v[32:33], off offset:96
	global_load_dwordx4 v[50:53], v[32:33], off offset:128
	global_load_dwordx4 v[54:57], v[32:33], off offset:160
	global_load_dwordx4 v[58:61], v[32:33], off offset:192
	global_load_dwordx4 v[62:65], v[32:33], off offset:224
	global_load_dwordx4 v[66:69], v[32:33], off offset:256
	global_load_dwordx4 v[70:73], v[32:33], off offset:288
	global_load_dwordx4 v[74:77], v[32:33], off offset:320
	global_load_dwordx4 v[78:81], v[32:33], off offset:352
	global_load_dwordx4 v[82:85], v[32:33], off offset:384
	global_load_dwordx4 v[86:89], v[32:33], off offset:416
	global_load_dwordx4 v[90:93], v[32:33], off offset:448
	global_load_dwordx4 v[94:97], v[32:33], off offset:480
	global_load_dwordx4 v[98:101], v[32:33], off offset:512
	global_load_dwordx4 v[102:105], v[32:33], off offset:544
	global_load_dwordx4 v[106:109], v[32:33], off offset:576
	global_load_dwordx4 v[110:113], v[32:33], off offset:608
	s_cmp_gt_i32 s27, 1
	s_cselect_b32 s8, 0xa000, 0
	s_add_u32 s8, s16, s8
	v_add_u32_e32 v0, 0, v170
	s_addc_u32 s9, s17, 0
	s_cmp_lt_i32 s27, 0
	s_waitcnt vmcnt(26)
	ds_write_b128 v0, v[16:19]
	ds_write_b128 v0, v[12:15] offset:16
	ds_write_b128 v0, v[8:11] offset:32
	ds_write_b128 v0, v[4:7] offset:48
	s_waitcnt vmcnt(22)
	ds_write_b128 v0, v[114:117] offset:64
	ds_write_b128 v0, v[28:31] offset:80
	ds_write_b128 v0, v[24:27] offset:96
	ds_write_b128 v0, v[20:23] offset:112
	s_waitcnt vmcnt(20)
	ds_write_b128 v0, v[122:125] offset:128
	ds_write_b128 v0, v[118:121] offset:144
	v_lshl_add_u64 v[4:5], s[8:9], 0, v[162:163]
	global_load_dwordx4 v[114:117], v[4:5], off offset:48
	global_load_dwordx4 v[118:121], v[4:5], off offset:32
	global_load_dwordx4 v[122:125], v[4:5], off offset:16
	global_load_dwordx4 v[126:129], v[4:5], off
	global_load_dwordx4 v[130:133], v[4:5], off offset:112
	global_load_dwordx4 v[134:137], v[4:5], off offset:96
	global_load_dwordx4 v[138:141], v[4:5], off offset:80
	global_load_dwordx4 v[142:145], v[4:5], off offset:64
	global_load_dwordx4 v[146:149], v[4:5], off offset:144
	global_load_dwordx4 v[150:153], v[4:5], off offset:128
	v_mov_b32_e32 v0, 0
	s_waitcnt lgkmcnt(0)
	s_barrier
	s_cbranch_scc1 .LBB0_416
	s_mov_b64 s[8:9], 0x14090
	s_mov_b32 s18, 1
	s_add_i32 s19, s27, 1
	v_lshl_add_u64 v[166:167], v[2:3], 0, s[8:9]
	v_mov_b32_e32 v165, 0xf149f2ca
	v_mov_b32_e32 v0, 0
	s_mov_b32 s28, 0
	s_mov_b32 s29, 0
	s_mov_b32 s8, 0
	s_add_i32 s30, s8, 1
	s_cmp_ge_i32 s30, s27
	s_cbranch_scc1 .LBB0_409
